# barrier: every 8th arriver of an XCD starts an L2 write-back early; early L1 invalidate
# speedup vs baseline: 1.0531x; 1.0531x over previous
; __device__ __forceinline__ unsigned xb_ld(unsigned* p)              { return __hip_atomic_load(p, __ATOMIC_RELAXED, __HIP_MEMORY_SCOPE_AGENT); }
; __device__ __forceinline__ unsigned xb_add(unsigned* p, unsigned v) { return __hip_atomic_fetch_add(p, v, __ATOMIC_RELAXED, __HIP_MEMORY_SCOPE_AGENT); }
; #define XB_SPIN(cond, bar) do { unsigned _sp = 0; while (cond) {   \
;     if ((++_sp & 255u) == 0u) { if (xb_ld(&(bar)[XB_TMO])) break; if (_sp > XB_SPIN_CAP) { atomicAdd(&(bar)[XB_TMO], 1u); break; } } } } while (0)
; __device__ __forceinline__ void xcd_barrier(const XcdBarrier& b) {
;     ...
;         const unsigned old = xb_add(&bar[XB_XSUB(b.x)], 1u);
;         const unsigned gen = old / nloc;
;         if (old + 1u == (gen + 1u) * nloc) {
;             __builtin_amdgcn_fence(__ATOMIC_RELEASE, "agent");
;             asm volatile("s_waitcnt vmcnt(0)" ::: "memory");
;             const unsigned og = xb_add(&bar[XB_TOP], 1u);
;             const unsigned tg = og / nx;
;             if (og + 1u == (tg + 1u) * nx) xb_add(&bar[XB_TOPGEN], 1u);
;             else XB_SPIN(xb_ld(&bar[XB_TOPGEN]) == tg, bar);
;             __builtin_amdgcn_fence(__ATOMIC_ACQUIRE, "agent");
;             xb_add(&bar[XB_XGEN(b.x)], 1u);
;             asm volatile("s_waitcnt vmcnt(0)" ::: "memory");
;         } else {
;             XB_SPIN(xb_ld(&bar[XB_XGEN(b.x)]) == gen, bar);
.LBB0_515:
	s_or_b64 exec, exec, s[6:7]
	v_cvt_f32_u32_e32 v5, v3
	s_waitcnt vmcnt(0)
	v_readfirstlane_b32 s2, v4
	v_sub_u32_e32 v4, 0, v3
	v_rcp_iflag_f32_e32 v5, v5
	v_add_u32_e32 v6, s2, v0
	v_mul_f32_e32 v5, 0x4f7ffffe, v5
	v_cvt_u32_f32_e32 v5, v5
	v_mul_lo_u32 v0, v4, v5
	v_mul_hi_u32 v0, v5, v0
	v_add_u32_e32 v0, v5, v0
	v_mul_hi_u32 v0, v6, v0
	v_mul_lo_u32 v4, v0, v3
	v_sub_u32_e32 v4, v6, v4
	v_add_u32_e32 v5, 1, v0
	v_cmp_ge_u32_e32 vcc, v4, v3
	s_nop 1
	v_cndmask_b32_e32 v0, v0, v5, vcc
	v_sub_u32_e32 v5, v4, v3
	v_cndmask_b32_e32 v4, v4, v5, vcc
	v_add_u32_e32 v5, 1, v0
	v_cmp_ge_u32_e32 vcc, v4, v3
	v_add_u32_e32 v4, 1, v6
	s_nop 0
	v_cndmask_b32_e32 v0, v0, v5, vcc
	v_mul_lo_u32 v5, v3, v0
	v_add_u32_e32 v3, v5, v3
	v_cmp_ne_u32_e32 vcc, v4, v3
	s_and_saveexec_b64 s[2:3], vcc
	s_xor_b64 s[6:7], exec, s[2:3]
	s_cbranch_execz .LBB0_529
	v_sub_u32_e32 v7, v6, v5
	v_and_b32_e32 v7, 7, v7
	v_cmp_eq_u32_e32 vcc, 0, v7
	s_cbranch_vccz .Lwb_skip
	buffer_wbl2 sc1
.Lwb_skip:
	v_readlane_b32 s2, v247, 14
	v_readlane_b32 s3, v247, 15
	s_waitcnt lgkmcnt(0)
	s_nop 3
	global_load_dword v2, v1, s[2:3] sc1
	s_waitcnt vmcnt(0)
	v_cmp_eq_u32_e32 vcc, v2, v0
	s_and_saveexec_b64 s[8:9], vcc
	s_cbranch_execz .LBB0_528
	s_mov_b32 s2, 1
	s_mov_b64 s[10:11], 0
	s_branch .LBB0_519
